# v41 + all s_setprio removed from the four K-loops
# baseline (speedup 1.0000x reference)
.LBB0_114:
	s_add_u32 s42, s4, s0
	s_addc_u32 s43, s5, s1
	s_add_u32 s42, s42, 0x100
	s_addc_u32 s43, s43, 0
	s_add_u32 s66, s20, s0
	s_addc_u32 s67, s21, s1
	s_add_i32 s70, 0, 0x10000
	s_cmpk_eq_i32 s0, 0xf00
	s_cselect_b32 s45, s25, s43
	s_cselect_b32 s44, s37, s42
	v_add_u32_e32 v155, s70, v151
	s_cselect_b32 s43, s29, s67
	s_cselect_b32 s42, s64, s66
	s_add_i32 s71, 0, 0x14000
	ds_read_b128 v[142:145], v155
	ds_read_b128 v[146:149], v155 offset:1024
	ds_read_b128 v[156:159], v155 offset:2048
	ds_read_b128 v[160:163], v155 offset:3072
	v_add_u32_e32 v155, s71, v151
	ds_read_b128 v[164:167], v155
	ds_read_b128 v[168:171], v155 offset:1024
	ds_read_b128 v[172:175], v155 offset:2048
	ds_read_b128 v[176:179], v155 offset:3072
	v_lshl_add_u64 v[222:223], v[138:139], 0, s[0:1]
	s_add_i32 m0, s46, 0xc000
	ds_read_b128 v[180:183], v154
	ds_read_b128 v[184:187], v154 offset:1024
	ds_read_b128 v[188:191], v154 offset:2048
	ds_read_b128 v[192:195], v154 offset:3072
	ds_read_b128 v[196:199], v154 offset:4096
	ds_read_b128 v[210:213], v154 offset:5120
	ds_read_b128 v[214:217], v154 offset:6144
	ds_read_b128 v[218:221], v154 offset:7168
	global_load_lds_dwordx4 v[222:223], off
	v_lshl_add_u64 v[222:223], v[140:141], 0, s[0:1]
	s_add_i32 m0, s46, 0xe000
	s_nop 0
	global_load_lds_dwordx4 v[222:223], off
	s_waitcnt vmcnt(8)
	s_waitcnt lgkmcnt(0)
	s_barrier
	v_mfma_f32_16x16x32_bf16 v[124:127], v[142:145], v[180:183], v[124:127]
	v_mfma_f32_16x16x32_bf16 v[120:123], v[156:159], v[180:183], v[120:123]
	v_mfma_f32_16x16x32_bf16 v[116:119], v[142:145], v[188:191], v[116:119]
	v_mfma_f32_16x16x32_bf16 v[112:115], v[156:159], v[188:191], v[112:115]
	v_mfma_f32_16x16x32_bf16 v[108:111], v[142:145], v[196:199], v[108:111]
	v_mfma_f32_16x16x32_bf16 v[104:107], v[156:159], v[196:199], v[104:107]
	v_mfma_f32_16x16x32_bf16 v[100:103], v[142:145], v[214:217], v[100:103]
	v_mfma_f32_16x16x32_bf16 v[96:99], v[156:159], v[214:217], v[96:99]
	v_mfma_f32_16x16x32_bf16 v[124:127], v[146:149], v[184:187], v[124:127]
	v_mfma_f32_16x16x32_bf16 v[120:123], v[160:163], v[184:187], v[120:123]
	v_mfma_f32_16x16x32_bf16 v[116:119], v[146:149], v[192:195], v[116:119]
	v_mfma_f32_16x16x32_bf16 v[112:115], v[160:163], v[192:195], v[112:115]
	v_mfma_f32_16x16x32_bf16 v[108:111], v[146:149], v[210:213], v[108:111]
	v_mfma_f32_16x16x32_bf16 v[104:107], v[160:163], v[210:213], v[104:107]
	v_mfma_f32_16x16x32_bf16 v[100:103], v[146:149], v[218:221], v[100:103]
	v_mfma_f32_16x16x32_bf16 v[96:99], v[160:163], v[218:221], v[96:99]
	v_mfma_f32_16x16x32_bf16 v[92:95], v[164:167], v[180:183], v[92:95]
	v_mfma_f32_16x16x32_bf16 v[88:91], v[172:175], v[180:183], v[88:91]
	v_mfma_f32_16x16x32_bf16 v[84:87], v[164:167], v[188:191], v[84:87]
	v_mfma_f32_16x16x32_bf16 v[80:83], v[172:175], v[188:191], v[80:83]
	v_mfma_f32_16x16x32_bf16 v[76:79], v[164:167], v[196:199], v[76:79]
	v_mfma_f32_16x16x32_bf16 v[72:75], v[172:175], v[196:199], v[72:75]
	v_mfma_f32_16x16x32_bf16 v[68:71], v[164:167], v[214:217], v[68:71]
	v_mfma_f32_16x16x32_bf16 v[64:67], v[172:175], v[214:217], v[64:67]
	v_mfma_f32_16x16x32_bf16 v[92:95], v[168:171], v[184:187], v[92:95]
	v_mfma_f32_16x16x32_bf16 v[88:91], v[176:179], v[184:187], v[88:91]
	v_mfma_f32_16x16x32_bf16 v[84:87], v[168:171], v[192:195], v[84:87]
	v_mfma_f32_16x16x32_bf16 v[80:83], v[176:179], v[192:195], v[80:83]
	v_mfma_f32_16x16x32_bf16 v[76:79], v[168:171], v[210:213], v[76:79]
	v_mfma_f32_16x16x32_bf16 v[72:75], v[176:179], v[210:213], v[72:75]
	v_mfma_f32_16x16x32_bf16 v[68:71], v[168:171], v[218:221], v[68:71]
	v_mfma_f32_16x16x32_bf16 v[64:67], v[176:179], v[218:221], v[64:67]
	s_barrier
	s_add_i32 s66, s70, s2
	v_lshl_add_u64 v[222:223], s[42:43], 0, v[204:205]
	s_mov_b32 m0, s66
	ds_read_b128 v[180:183], v154 offset:16384
	ds_read_b128 v[184:187], v154 offset:17408
	ds_read_b128 v[188:191], v154 offset:18432
	ds_read_b128 v[192:195], v154 offset:19456
	ds_read_b128 v[196:199], v154 offset:20480
	ds_read_b128 v[210:213], v154 offset:21504
	ds_read_b128 v[214:217], v154 offset:22528
	ds_read_b128 v[218:221], v154 offset:23552
	global_load_lds_dwordx4 v[222:223], off
	s_add_i32 m0, s66, 0x2000
	s_add_u32 s66, s42, 0x80000
	v_lshl_add_u64 v[224:225], s[42:43], 0, v[128:129]
	s_addc_u32 s67, s43, 0
	s_add_i32 s70, s71, s2
	global_load_lds_dwordx4 v[224:225], off
	v_lshl_add_u64 v[226:227], s[66:67], 0, v[204:205]
	s_mov_b32 m0, s70
	v_lshl_add_u64 v[228:229], s[44:45], 0, v[130:131]
	global_load_lds_dwordx4 v[226:227], off
	v_lshl_add_u64 v[226:227], s[66:67], 0, v[128:129]
	s_add_i32 m0, s70, 0x2000
	s_nop 0
	global_load_lds_dwordx4 v[226:227], off
	v_lshl_add_u64 v[226:227], s[44:45], 0, v[132:133]
	s_mov_b32 m0, s46
	s_nop 0
	global_load_lds_dwordx4 v[226:227], off
	s_mov_b32 m0, s47
	s_nop 0
	global_load_lds_dwordx4 v[228:229], off
	s_waitcnt vmcnt(8)
	s_waitcnt lgkmcnt(0)
	s_barrier
	v_mfma_f32_16x16x32_bf16 v[60:63], v[142:145], v[180:183], v[60:63]
	v_mfma_f32_16x16x32_bf16 v[56:59], v[156:159], v[180:183], v[56:59]
	v_mfma_f32_16x16x32_bf16 v[52:55], v[142:145], v[188:191], v[52:55]
	v_mfma_f32_16x16x32_bf16 v[48:51], v[156:159], v[188:191], v[48:51]
	v_mfma_f32_16x16x32_bf16 v[44:47], v[142:145], v[196:199], v[44:47]
	v_mfma_f32_16x16x32_bf16 v[40:43], v[156:159], v[196:199], v[40:43]
	v_mfma_f32_16x16x32_bf16 v[36:39], v[142:145], v[214:217], v[36:39]
	v_mfma_f32_16x16x32_bf16 v[32:35], v[156:159], v[214:217], v[32:35]
	v_mfma_f32_16x16x32_bf16 v[60:63], v[146:149], v[184:187], v[60:63]
	v_mfma_f32_16x16x32_bf16 v[56:59], v[160:163], v[184:187], v[56:59]
	v_mfma_f32_16x16x32_bf16 v[52:55], v[146:149], v[192:195], v[52:55]
	v_mfma_f32_16x16x32_bf16 v[48:51], v[160:163], v[192:195], v[48:51]
	v_mfma_f32_16x16x32_bf16 v[44:47], v[146:149], v[210:213], v[44:47]
	v_mfma_f32_16x16x32_bf16 v[40:43], v[160:163], v[210:213], v[40:43]
	v_mfma_f32_16x16x32_bf16 v[36:39], v[146:149], v[218:221], v[36:39]
	v_mfma_f32_16x16x32_bf16 v[32:35], v[160:163], v[218:221], v[32:35]
	v_mfma_f32_16x16x32_bf16 v[28:31], v[164:167], v[180:183], v[28:31]
	v_mfma_f32_16x16x32_bf16 v[24:27], v[172:175], v[180:183], v[24:27]
	v_mfma_f32_16x16x32_bf16 v[20:23], v[164:167], v[188:191], v[20:23]
	v_mfma_f32_16x16x32_bf16 v[16:19], v[172:175], v[188:191], v[16:19]
	v_mfma_f32_16x16x32_bf16 v[12:15], v[164:167], v[196:199], v[12:15]
	v_mfma_f32_16x16x32_bf16 v[8:11], v[172:175], v[196:199], v[8:11]
	v_mfma_f32_16x16x32_bf16 v[4:7], v[164:167], v[214:217], v[4:7]
	v_mfma_f32_16x16x32_bf16 v[0:3], v[172:175], v[214:217], v[0:3]
	v_mfma_f32_16x16x32_bf16 v[28:31], v[168:171], v[184:187], v[28:31]
	v_mfma_f32_16x16x32_bf16 v[24:27], v[176:179], v[184:187], v[24:27]
	v_mfma_f32_16x16x32_bf16 v[20:23], v[168:171], v[192:195], v[20:23]
	v_mfma_f32_16x16x32_bf16 v[16:19], v[176:179], v[192:195], v[16:19]
	v_mfma_f32_16x16x32_bf16 v[12:15], v[168:171], v[210:213], v[12:15]
	v_mfma_f32_16x16x32_bf16 v[8:11], v[176:179], v[210:213], v[8:11]
	v_mfma_f32_16x16x32_bf16 v[4:7], v[168:171], v[218:221], v[4:7]
	v_mfma_f32_16x16x32_bf16 v[0:3], v[176:179], v[218:221], v[0:3]
	s_barrier
	s_add_i32 s66, 0, 0x18000
	v_add_u32_e32 v155, s66, v151
	s_add_i32 s67, 0, 0x1c000
	ds_read_b128 v[142:145], v155
	ds_read_b128 v[146:149], v155 offset:1024
	ds_read_b128 v[156:159], v155 offset:2048
	ds_read_b128 v[160:163], v155 offset:3072
	v_add_u32_e32 v155, s67, v151
	ds_read_b128 v[164:167], v155
	ds_read_b128 v[168:171], v155 offset:1024
	ds_read_b128 v[172:175], v155 offset:2048
	ds_read_b128 v[176:179], v155 offset:3072
	s_add_u32 s44, s44, 0x80000
	s_addc_u32 s45, s45, 0
	s_mov_b32 m0, s48
	v_lshl_add_u64 v[230:231], s[44:45], 0, v[132:133]
	ds_read_b128 v[180:183], v154 offset:32768
	ds_read_b128 v[184:187], v154 offset:33792
	ds_read_b128 v[188:191], v154 offset:34816
	ds_read_b128 v[192:195], v154 offset:35840
	ds_read_b128 v[196:199], v154 offset:36864
	ds_read_b128 v[210:213], v154 offset:37888
	ds_read_b128 v[214:217], v154 offset:38912
	ds_read_b128 v[218:221], v154 offset:39936
	global_load_lds_dwordx4 v[230:231], off
	v_lshl_add_u64 v[230:231], s[44:45], 0, v[130:131]
	s_mov_b32 m0, s49
	s_nop 0
	global_load_lds_dwordx4 v[230:231], off
	s_waitcnt vmcnt(8)
	s_waitcnt lgkmcnt(0)
	s_barrier
	v_mfma_f32_16x16x32_bf16 v[124:127], v[142:145], v[180:183], v[124:127]
	v_mfma_f32_16x16x32_bf16 v[120:123], v[156:159], v[180:183], v[120:123]
	v_mfma_f32_16x16x32_bf16 v[116:119], v[142:145], v[188:191], v[116:119]
	v_mfma_f32_16x16x32_bf16 v[112:115], v[156:159], v[188:191], v[112:115]
	v_mfma_f32_16x16x32_bf16 v[108:111], v[142:145], v[196:199], v[108:111]
	v_mfma_f32_16x16x32_bf16 v[104:107], v[156:159], v[196:199], v[104:107]
	v_mfma_f32_16x16x32_bf16 v[100:103], v[142:145], v[214:217], v[100:103]
	v_mfma_f32_16x16x32_bf16 v[96:99], v[156:159], v[214:217], v[96:99]
	v_mfma_f32_16x16x32_bf16 v[124:127], v[146:149], v[184:187], v[124:127]
	v_mfma_f32_16x16x32_bf16 v[120:123], v[160:163], v[184:187], v[120:123]
	v_mfma_f32_16x16x32_bf16 v[116:119], v[146:149], v[192:195], v[116:119]
	v_mfma_f32_16x16x32_bf16 v[112:115], v[160:163], v[192:195], v[112:115]
	v_mfma_f32_16x16x32_bf16 v[108:111], v[146:149], v[210:213], v[108:111]
	v_mfma_f32_16x16x32_bf16 v[104:107], v[160:163], v[210:213], v[104:107]
	v_mfma_f32_16x16x32_bf16 v[100:103], v[146:149], v[218:221], v[100:103]
	v_mfma_f32_16x16x32_bf16 v[96:99], v[160:163], v[218:221], v[96:99]
	v_mfma_f32_16x16x32_bf16 v[92:95], v[164:167], v[180:183], v[92:95]
	v_mfma_f32_16x16x32_bf16 v[88:91], v[172:175], v[180:183], v[88:91]
	v_mfma_f32_16x16x32_bf16 v[84:87], v[164:167], v[188:191], v[84:87]
	v_mfma_f32_16x16x32_bf16 v[80:83], v[172:175], v[188:191], v[80:83]
	v_mfma_f32_16x16x32_bf16 v[76:79], v[164:167], v[196:199], v[76:79]
	v_mfma_f32_16x16x32_bf16 v[72:75], v[172:175], v[196:199], v[72:75]
	v_mfma_f32_16x16x32_bf16 v[68:71], v[164:167], v[214:217], v[68:71]
	v_mfma_f32_16x16x32_bf16 v[64:67], v[172:175], v[214:217], v[64:67]
	v_mfma_f32_16x16x32_bf16 v[92:95], v[168:171], v[184:187], v[92:95]
	v_mfma_f32_16x16x32_bf16 v[88:91], v[176:179], v[184:187], v[88:91]
	v_mfma_f32_16x16x32_bf16 v[84:87], v[168:171], v[192:195], v[84:87]
	v_mfma_f32_16x16x32_bf16 v[80:83], v[176:179], v[192:195], v[80:83]
	v_mfma_f32_16x16x32_bf16 v[76:79], v[168:171], v[210:213], v[76:79]
	v_mfma_f32_16x16x32_bf16 v[72:75], v[176:179], v[210:213], v[72:75]
	v_mfma_f32_16x16x32_bf16 v[68:71], v[168:171], v[218:221], v[68:71]
	v_mfma_f32_16x16x32_bf16 v[64:67], v[176:179], v[218:221], v[64:67]
	s_barrier
	s_add_i32 s44, s66, s2
	v_lshl_add_u64 v[222:223], v[222:223], 0, s[12:13]
	s_mov_b32 m0, s44
	ds_read_b128 v[180:183], v154 offset:49152
	ds_read_b128 v[184:187], v154 offset:50176
	ds_read_b128 v[188:191], v154 offset:51200
	ds_read_b128 v[192:195], v154 offset:52224
	ds_read_b128 v[196:199], v154 offset:53248
	ds_read_b128 v[210:213], v154 offset:54272
	ds_read_b128 v[214:217], v154 offset:55296
	ds_read_b128 v[218:221], v154 offset:56320
	global_load_lds_dwordx4 v[222:223], off
	s_add_i32 m0, s44, 0x2000
	s_add_u32 s42, s42, 0x80080
	v_lshl_add_u64 v[222:223], v[224:225], 0, s[12:13]
	s_addc_u32 s43, s43, 0
	s_add_i32 s44, s67, s2
	global_load_lds_dwordx4 v[222:223], off
	v_lshl_add_u64 v[222:223], s[42:43], 0, v[204:205]
	s_mov_b32 m0, s44
	s_nop 0
	global_load_lds_dwordx4 v[222:223], off
	v_lshl_add_u64 v[222:223], s[42:43], 0, v[128:129]
	s_add_i32 m0, s44, 0x2000
	s_nop 0
	global_load_lds_dwordx4 v[222:223], off
	v_lshl_add_u64 v[222:223], v[226:227], 0, s[12:13]
	s_mov_b32 m0, s50
	s_nop 0
	global_load_lds_dwordx4 v[222:223], off
	v_lshl_add_u64 v[222:223], v[228:229], 0, s[12:13]
	s_mov_b32 m0, s51
	s_nop 0
	global_load_lds_dwordx4 v[222:223], off
	s_waitcnt vmcnt(8)
	s_waitcnt lgkmcnt(0)
	s_barrier
	v_mfma_f32_16x16x32_bf16 v[60:63], v[142:145], v[180:183], v[60:63]
	v_mfma_f32_16x16x32_bf16 v[56:59], v[156:159], v[180:183], v[56:59]
	v_mfma_f32_16x16x32_bf16 v[52:55], v[142:145], v[188:191], v[52:55]
	v_mfma_f32_16x16x32_bf16 v[48:51], v[156:159], v[188:191], v[48:51]
	v_mfma_f32_16x16x32_bf16 v[44:47], v[142:145], v[196:199], v[44:47]
	v_mfma_f32_16x16x32_bf16 v[40:43], v[156:159], v[196:199], v[40:43]
	v_mfma_f32_16x16x32_bf16 v[36:39], v[142:145], v[214:217], v[36:39]
	v_mfma_f32_16x16x32_bf16 v[32:35], v[156:159], v[214:217], v[32:35]
	v_mfma_f32_16x16x32_bf16 v[60:63], v[146:149], v[184:187], v[60:63]
	v_mfma_f32_16x16x32_bf16 v[56:59], v[160:163], v[184:187], v[56:59]
	v_mfma_f32_16x16x32_bf16 v[52:55], v[146:149], v[192:195], v[52:55]
	v_mfma_f32_16x16x32_bf16 v[48:51], v[160:163], v[192:195], v[48:51]
	v_mfma_f32_16x16x32_bf16 v[44:47], v[146:149], v[210:213], v[44:47]
	v_mfma_f32_16x16x32_bf16 v[40:43], v[160:163], v[210:213], v[40:43]
	v_mfma_f32_16x16x32_bf16 v[36:39], v[146:149], v[218:221], v[36:39]
	v_mfma_f32_16x16x32_bf16 v[32:35], v[160:163], v[218:221], v[32:35]
	v_mfma_f32_16x16x32_bf16 v[28:31], v[164:167], v[180:183], v[28:31]
	v_mfma_f32_16x16x32_bf16 v[24:27], v[172:175], v[180:183], v[24:27]
	v_mfma_f32_16x16x32_bf16 v[20:23], v[164:167], v[188:191], v[20:23]
	v_mfma_f32_16x16x32_bf16 v[16:19], v[172:175], v[188:191], v[16:19]
	v_mfma_f32_16x16x32_bf16 v[12:15], v[164:167], v[196:199], v[12:15]
	v_mfma_f32_16x16x32_bf16 v[8:11], v[172:175], v[196:199], v[8:11]
	v_mfma_f32_16x16x32_bf16 v[4:7], v[164:167], v[214:217], v[4:7]
	v_mfma_f32_16x16x32_bf16 v[0:3], v[172:175], v[214:217], v[0:3]
	v_mfma_f32_16x16x32_bf16 v[28:31], v[168:171], v[184:187], v[28:31]
	v_mfma_f32_16x16x32_bf16 v[24:27], v[176:179], v[184:187], v[24:27]
	v_mfma_f32_16x16x32_bf16 v[20:23], v[168:171], v[192:195], v[20:23]
	v_mfma_f32_16x16x32_bf16 v[16:19], v[176:179], v[192:195], v[16:19]
	v_mfma_f32_16x16x32_bf16 v[12:15], v[168:171], v[210:213], v[12:15]
	v_mfma_f32_16x16x32_bf16 v[8:11], v[176:179], v[210:213], v[8:11]
	v_mfma_f32_16x16x32_bf16 v[4:7], v[168:171], v[218:221], v[4:7]
	v_mfma_f32_16x16x32_bf16 v[0:3], v[176:179], v[218:221], v[0:3]
	s_barrier
	s_add_i32 s65, s65, 2
	s_add_u32 s0, s0, 0x100
	s_addc_u32 s1, s1, 0
	s_cmp_gt_u32 s65, 29
	s_cbranch_scc0 .LBB0_114

.LBB0_183:
	s_add_i32 s25, s4, 2
	s_add_u32 s28, s0, 0x80
	s_addc_u32 s5, s1, 0
	s_add_i32 s36, 0, 0x10000
	s_cmp_eq_u32 s63, s4
	s_cselect_b32 s5, s49, s5
	s_cselect_b32 s4, s48, s28
	s_cselect_b32 s29, s51, s22
	s_cselect_b32 s28, s50, s21
	s_add_i32 s37, 0, 0x14000
	v_add_u32_e32 v100, s36, v249
	v_add_u32_e32 v156, s37, v249
	ds_read_b128 v[88:91], v100
	ds_read_b128 v[92:95], v100 offset:1024
	ds_read_b128 v[96:99], v100 offset:2048
	ds_read_b128 v[100:103], v100 offset:3072
	s_waitcnt lgkmcnt(0)
	ds_read_b128 v[144:147], v156
	ds_read_b128 v[148:151], v156 offset:1024
	ds_read_b128 v[152:155], v156 offset:2048
	ds_read_b128 v[156:159], v156 offset:3072
	v_lshl_add_u64 v[192:193], s[0:1], 0, v[216:217]
	s_add_i32 m0, s3, 0xc000
	ds_read_b128 v[160:163], v251
	ds_read_b128 v[164:167], v251 offset:1024
	ds_read_b128 v[168:171], v251 offset:2048
	ds_read_b128 v[172:175], v251 offset:3072
	ds_read_b128 v[176:179], v251 offset:4096
	ds_read_b128 v[180:183], v251 offset:5120
	ds_read_b128 v[184:187], v251 offset:6144
	ds_read_b128 v[188:191], v251 offset:7168
	global_load_lds_dwordx4 v[192:193], off
	v_lshl_add_u64 v[192:193], s[0:1], 0, v[218:219]
	s_add_i32 m0, s3, 0xe000
	s_nop 0
	global_load_lds_dwordx4 v[192:193], off
	s_waitcnt vmcnt(8)
	s_waitcnt lgkmcnt(0)
	s_barrier
	v_mfma_f32_16x16x32_bf16 v[140:143], v[88:91], v[160:163], v[140:143]
	v_mfma_f32_16x16x32_bf16 v[136:139], v[96:99], v[160:163], v[136:139]
	v_mfma_f32_16x16x32_bf16 v[124:127], v[88:91], v[168:171], v[124:127]
	v_mfma_f32_16x16x32_bf16 v[120:123], v[96:99], v[168:171], v[120:123]
	v_mfma_f32_16x16x32_bf16 v[108:111], v[88:91], v[176:179], v[108:111]
	v_mfma_f32_16x16x32_bf16 v[104:107], v[96:99], v[176:179], v[104:107]
	v_mfma_f32_16x16x32_bf16 v[76:79], v[88:91], v[184:187], v[76:79]
	v_mfma_f32_16x16x32_bf16 v[72:75], v[96:99], v[184:187], v[72:75]
	v_mfma_f32_16x16x32_bf16 v[140:143], v[92:95], v[164:167], v[140:143]
	v_mfma_f32_16x16x32_bf16 v[136:139], v[100:103], v[164:167], v[136:139]
	v_mfma_f32_16x16x32_bf16 v[124:127], v[92:95], v[172:175], v[124:127]
	v_mfma_f32_16x16x32_bf16 v[120:123], v[100:103], v[172:175], v[120:123]
	v_mfma_f32_16x16x32_bf16 v[108:111], v[92:95], v[180:183], v[108:111]
	v_mfma_f32_16x16x32_bf16 v[104:107], v[100:103], v[180:183], v[104:107]
	v_mfma_f32_16x16x32_bf16 v[76:79], v[92:95], v[188:191], v[76:79]
	v_mfma_f32_16x16x32_bf16 v[72:75], v[100:103], v[188:191], v[72:75]
	v_mfma_f32_16x16x32_bf16 v[132:135], v[144:147], v[160:163], v[132:135]
	v_mfma_f32_16x16x32_bf16 v[128:131], v[152:155], v[160:163], v[128:131]
	v_mfma_f32_16x16x32_bf16 v[116:119], v[144:147], v[168:171], v[116:119]
	v_mfma_f32_16x16x32_bf16 v[112:115], v[152:155], v[168:171], v[112:115]
	v_mfma_f32_16x16x32_bf16 v[84:87], v[144:147], v[176:179], v[84:87]
	v_mfma_f32_16x16x32_bf16 v[80:83], v[152:155], v[176:179], v[80:83]
	v_mfma_f32_16x16x32_bf16 v[68:71], v[144:147], v[184:187], v[68:71]
	v_mfma_f32_16x16x32_bf16 v[64:67], v[152:155], v[184:187], v[64:67]
	v_mfma_f32_16x16x32_bf16 v[132:135], v[148:151], v[164:167], v[132:135]
	v_mfma_f32_16x16x32_bf16 v[128:131], v[156:159], v[164:167], v[128:131]
	v_mfma_f32_16x16x32_bf16 v[116:119], v[148:151], v[172:175], v[116:119]
	v_mfma_f32_16x16x32_bf16 v[112:115], v[156:159], v[172:175], v[112:115]
	v_mfma_f32_16x16x32_bf16 v[84:87], v[148:151], v[180:183], v[84:87]
	v_mfma_f32_16x16x32_bf16 v[80:83], v[156:159], v[180:183], v[80:83]
	v_mfma_f32_16x16x32_bf16 v[68:71], v[148:151], v[188:191], v[68:71]
	v_mfma_f32_16x16x32_bf16 v[64:67], v[156:159], v[188:191], v[64:67]
	s_barrier
	s_add_i32 s36, s36, s2
	v_lshl_add_u64 v[192:193], s[28:29], 0, v[204:205]
	s_mov_b32 m0, s36
	ds_read_b128 v[160:163], v251 offset:16384
	ds_read_b128 v[164:167], v251 offset:17408
	ds_read_b128 v[168:171], v251 offset:18432
	ds_read_b128 v[172:175], v251 offset:19456
	ds_read_b128 v[176:179], v251 offset:20480
	ds_read_b128 v[180:183], v251 offset:21504
	ds_read_b128 v[184:187], v251 offset:22528
	ds_read_b128 v[188:191], v251 offset:23552
	global_load_lds_dwordx4 v[192:193], off
	s_add_i32 m0, s36, 0x2000
	v_lshl_add_u64 v[194:195], s[28:29], 0, v[210:211]
	s_add_u32 s28, s28, s10
	s_addc_u32 s29, s29, 0
	s_add_i32 s36, s37, s2
	global_load_lds_dwordx4 v[194:195], off
	v_lshl_add_u64 v[196:197], s[28:29], 0, v[204:205]
	s_mov_b32 m0, s36
	v_lshl_add_u64 v[198:199], s[28:29], 0, v[210:211]
	global_load_lds_dwordx4 v[196:197], off
	s_add_i32 m0, s36, 0x2000
	v_lshl_add_u64 v[220:221], s[4:5], 0, v[214:215]
	global_load_lds_dwordx4 v[198:199], off
	s_mov_b32 m0, s3
	v_lshl_add_u64 v[222:223], s[4:5], 0, v[212:213]
	global_load_lds_dwordx4 v[220:221], off
	s_mov_b32 m0, s52
	s_nop 0
	global_load_lds_dwordx4 v[222:223], off
	s_waitcnt vmcnt(8)
	s_waitcnt lgkmcnt(0)
	s_barrier
	v_mfma_f32_16x16x32_bf16 v[60:63], v[88:91], v[160:163], v[60:63]
	v_mfma_f32_16x16x32_bf16 v[56:59], v[96:99], v[160:163], v[56:59]
	v_mfma_f32_16x16x32_bf16 v[44:47], v[88:91], v[168:171], v[44:47]
	v_mfma_f32_16x16x32_bf16 v[40:43], v[96:99], v[168:171], v[40:43]
	v_mfma_f32_16x16x32_bf16 v[28:31], v[88:91], v[176:179], v[28:31]
	v_mfma_f32_16x16x32_bf16 v[24:27], v[96:99], v[176:179], v[24:27]
	v_mfma_f32_16x16x32_bf16 v[12:15], v[88:91], v[184:187], v[12:15]
	v_mfma_f32_16x16x32_bf16 v[8:11], v[96:99], v[184:187], v[8:11]
	v_mfma_f32_16x16x32_bf16 v[60:63], v[92:95], v[164:167], v[60:63]
	v_mfma_f32_16x16x32_bf16 v[56:59], v[100:103], v[164:167], v[56:59]
	v_mfma_f32_16x16x32_bf16 v[44:47], v[92:95], v[172:175], v[44:47]
	v_mfma_f32_16x16x32_bf16 v[40:43], v[100:103], v[172:175], v[40:43]
	v_mfma_f32_16x16x32_bf16 v[28:31], v[92:95], v[180:183], v[28:31]
	v_mfma_f32_16x16x32_bf16 v[24:27], v[100:103], v[180:183], v[24:27]
	v_mfma_f32_16x16x32_bf16 v[12:15], v[92:95], v[188:191], v[12:15]
	v_mfma_f32_16x16x32_bf16 v[8:11], v[100:103], v[188:191], v[8:11]
	v_mfma_f32_16x16x32_bf16 v[52:55], v[144:147], v[160:163], v[52:55]
	v_mfma_f32_16x16x32_bf16 v[48:51], v[152:155], v[160:163], v[48:51]
	v_mfma_f32_16x16x32_bf16 v[36:39], v[144:147], v[168:171], v[36:39]
	v_mfma_f32_16x16x32_bf16 v[32:35], v[152:155], v[168:171], v[32:35]
	v_mfma_f32_16x16x32_bf16 v[20:23], v[144:147], v[176:179], v[20:23]
	v_mfma_f32_16x16x32_bf16 v[16:19], v[152:155], v[176:179], v[16:19]
	v_mfma_f32_16x16x32_bf16 v[4:7], v[144:147], v[184:187], v[4:7]
	v_mfma_f32_16x16x32_bf16 v[0:3], v[152:155], v[184:187], v[0:3]
	v_mfma_f32_16x16x32_bf16 v[52:55], v[148:151], v[164:167], v[52:55]
	v_mfma_f32_16x16x32_bf16 v[48:51], v[156:159], v[164:167], v[48:51]
	v_mfma_f32_16x16x32_bf16 v[36:39], v[148:151], v[172:175], v[36:39]
	v_mfma_f32_16x16x32_bf16 v[32:35], v[156:159], v[172:175], v[32:35]
	v_mfma_f32_16x16x32_bf16 v[20:23], v[148:151], v[180:183], v[20:23]
	v_mfma_f32_16x16x32_bf16 v[16:19], v[156:159], v[180:183], v[16:19]
	v_mfma_f32_16x16x32_bf16 v[4:7], v[148:151], v[188:191], v[4:7]
	v_mfma_f32_16x16x32_bf16 v[0:3], v[156:159], v[188:191], v[0:3]
	s_barrier
	s_add_i32 s28, 0, 0x18000
	s_add_i32 s29, 0, 0x1c000
	v_add_u32_e32 v100, s28, v249
	v_add_u32_e32 v156, s29, v249
	ds_read_b128 v[88:91], v100
	ds_read_b128 v[92:95], v100 offset:1024
	ds_read_b128 v[96:99], v100 offset:2048
	ds_read_b128 v[100:103], v100 offset:3072
	ds_read_b128 v[144:147], v156
	ds_read_b128 v[148:151], v156 offset:1024
	ds_read_b128 v[152:155], v156 offset:2048
	ds_read_b128 v[156:159], v156 offset:3072
	s_add_u32 s4, s4, s10
	s_addc_u32 s5, s5, 0
	s_mov_b32 m0, s53
	v_lshl_add_u64 v[224:225], s[4:5], 0, v[214:215]
	ds_read_b128 v[160:163], v251 offset:32768
	ds_read_b128 v[164:167], v251 offset:33792
	ds_read_b128 v[168:171], v251 offset:34816
	ds_read_b128 v[172:175], v251 offset:35840
	ds_read_b128 v[176:179], v251 offset:36864
	ds_read_b128 v[180:183], v251 offset:37888
	ds_read_b128 v[184:187], v251 offset:38912
	ds_read_b128 v[188:191], v251 offset:39936
	global_load_lds_dwordx4 v[224:225], off
	v_lshl_add_u64 v[224:225], s[4:5], 0, v[212:213]
	s_mov_b32 m0, s54
	s_nop 0
	global_load_lds_dwordx4 v[224:225], off
	s_waitcnt vmcnt(8)
	s_waitcnt lgkmcnt(0)
	s_barrier
	v_mfma_f32_16x16x32_bf16 v[140:143], v[88:91], v[160:163], v[140:143]
	v_mfma_f32_16x16x32_bf16 v[136:139], v[96:99], v[160:163], v[136:139]
	v_mfma_f32_16x16x32_bf16 v[124:127], v[88:91], v[168:171], v[124:127]
	v_mfma_f32_16x16x32_bf16 v[120:123], v[96:99], v[168:171], v[120:123]
	v_mfma_f32_16x16x32_bf16 v[108:111], v[88:91], v[176:179], v[108:111]
	v_mfma_f32_16x16x32_bf16 v[104:107], v[96:99], v[176:179], v[104:107]
	v_mfma_f32_16x16x32_bf16 v[76:79], v[88:91], v[184:187], v[76:79]
	v_mfma_f32_16x16x32_bf16 v[72:75], v[96:99], v[184:187], v[72:75]
	v_mfma_f32_16x16x32_bf16 v[140:143], v[92:95], v[164:167], v[140:143]
	v_mfma_f32_16x16x32_bf16 v[136:139], v[100:103], v[164:167], v[136:139]
	v_mfma_f32_16x16x32_bf16 v[124:127], v[92:95], v[172:175], v[124:127]
	v_mfma_f32_16x16x32_bf16 v[120:123], v[100:103], v[172:175], v[120:123]
	v_mfma_f32_16x16x32_bf16 v[108:111], v[92:95], v[180:183], v[108:111]
	v_mfma_f32_16x16x32_bf16 v[104:107], v[100:103], v[180:183], v[104:107]
	v_mfma_f32_16x16x32_bf16 v[76:79], v[92:95], v[188:191], v[76:79]
	v_mfma_f32_16x16x32_bf16 v[72:75], v[100:103], v[188:191], v[72:75]
	v_mfma_f32_16x16x32_bf16 v[132:135], v[144:147], v[160:163], v[132:135]
	v_mfma_f32_16x16x32_bf16 v[128:131], v[152:155], v[160:163], v[128:131]
	v_mfma_f32_16x16x32_bf16 v[116:119], v[144:147], v[168:171], v[116:119]
	v_mfma_f32_16x16x32_bf16 v[112:115], v[152:155], v[168:171], v[112:115]
	v_mfma_f32_16x16x32_bf16 v[84:87], v[144:147], v[176:179], v[84:87]
	v_mfma_f32_16x16x32_bf16 v[80:83], v[152:155], v[176:179], v[80:83]
	v_mfma_f32_16x16x32_bf16 v[68:71], v[144:147], v[184:187], v[68:71]
	v_mfma_f32_16x16x32_bf16 v[64:67], v[152:155], v[184:187], v[64:67]
	v_mfma_f32_16x16x32_bf16 v[132:135], v[148:151], v[164:167], v[132:135]
	v_mfma_f32_16x16x32_bf16 v[128:131], v[156:159], v[164:167], v[128:131]
	v_mfma_f32_16x16x32_bf16 v[116:119], v[148:151], v[172:175], v[116:119]
	v_mfma_f32_16x16x32_bf16 v[112:115], v[156:159], v[172:175], v[112:115]
	v_mfma_f32_16x16x32_bf16 v[84:87], v[148:151], v[180:183], v[84:87]
	v_mfma_f32_16x16x32_bf16 v[80:83], v[156:159], v[180:183], v[80:83]
	v_mfma_f32_16x16x32_bf16 v[68:71], v[148:151], v[188:191], v[68:71]
	v_mfma_f32_16x16x32_bf16 v[64:67], v[156:159], v[188:191], v[64:67]
	s_barrier
	s_add_i32 s4, s28, s2
	v_lshl_add_u64 v[192:193], v[192:193], 0, s[12:13]
	s_mov_b32 m0, s4
	ds_read_b128 v[160:163], v251 offset:49152
	ds_read_b128 v[164:167], v251 offset:50176
	ds_read_b128 v[168:171], v251 offset:51200
	ds_read_b128 v[172:175], v251 offset:52224
	ds_read_b128 v[176:179], v251 offset:53248
	ds_read_b128 v[180:183], v251 offset:54272
	ds_read_b128 v[184:187], v251 offset:55296
	ds_read_b128 v[188:191], v251 offset:56320
	global_load_lds_dwordx4 v[192:193], off
	v_lshl_add_u64 v[192:193], v[194:195], 0, s[12:13]
	s_add_i32 m0, s4, 0x2000
	s_add_i32 s4, s29, s2
	global_load_lds_dwordx4 v[192:193], off
	v_lshl_add_u64 v[192:193], v[196:197], 0, s[12:13]
	s_mov_b32 m0, s4
	s_nop 0
	global_load_lds_dwordx4 v[192:193], off
	v_lshl_add_u64 v[192:193], v[198:199], 0, s[12:13]
	s_add_i32 m0, s4, 0x2000
	s_nop 0
	global_load_lds_dwordx4 v[192:193], off
	v_lshl_add_u64 v[192:193], v[220:221], 0, s[12:13]
	s_mov_b32 m0, s55
	s_nop 0
	global_load_lds_dwordx4 v[192:193], off
	v_lshl_add_u64 v[192:193], v[222:223], 0, s[12:13]
	s_mov_b32 m0, s56
	s_nop 0
	global_load_lds_dwordx4 v[192:193], off
	s_waitcnt vmcnt(8)
	s_waitcnt lgkmcnt(0)
	s_barrier
	v_mfma_f32_16x16x32_bf16 v[60:63], v[88:91], v[160:163], v[60:63]
	v_mfma_f32_16x16x32_bf16 v[56:59], v[96:99], v[160:163], v[56:59]
	v_mfma_f32_16x16x32_bf16 v[44:47], v[88:91], v[168:171], v[44:47]
	v_mfma_f32_16x16x32_bf16 v[40:43], v[96:99], v[168:171], v[40:43]
	v_mfma_f32_16x16x32_bf16 v[28:31], v[88:91], v[176:179], v[28:31]
	v_mfma_f32_16x16x32_bf16 v[24:27], v[96:99], v[176:179], v[24:27]
	v_mfma_f32_16x16x32_bf16 v[12:15], v[88:91], v[184:187], v[12:15]
	v_mfma_f32_16x16x32_bf16 v[8:11], v[96:99], v[184:187], v[8:11]
	v_mfma_f32_16x16x32_bf16 v[60:63], v[92:95], v[164:167], v[60:63]
	v_mfma_f32_16x16x32_bf16 v[56:59], v[100:103], v[164:167], v[56:59]
	v_mfma_f32_16x16x32_bf16 v[44:47], v[92:95], v[172:175], v[44:47]
	v_mfma_f32_16x16x32_bf16 v[40:43], v[100:103], v[172:175], v[40:43]
	v_mfma_f32_16x16x32_bf16 v[28:31], v[92:95], v[180:183], v[28:31]
	v_mfma_f32_16x16x32_bf16 v[24:27], v[100:103], v[180:183], v[24:27]
	v_mfma_f32_16x16x32_bf16 v[12:15], v[92:95], v[188:191], v[12:15]
	v_mfma_f32_16x16x32_bf16 v[8:11], v[100:103], v[188:191], v[8:11]
	v_mfma_f32_16x16x32_bf16 v[52:55], v[144:147], v[160:163], v[52:55]
	v_mfma_f32_16x16x32_bf16 v[48:51], v[152:155], v[160:163], v[48:51]
	v_mfma_f32_16x16x32_bf16 v[36:39], v[144:147], v[168:171], v[36:39]
	v_mfma_f32_16x16x32_bf16 v[32:35], v[152:155], v[168:171], v[32:35]
	v_mfma_f32_16x16x32_bf16 v[20:23], v[144:147], v[176:179], v[20:23]
	v_mfma_f32_16x16x32_bf16 v[16:19], v[152:155], v[176:179], v[16:19]
	v_mfma_f32_16x16x32_bf16 v[4:7], v[144:147], v[184:187], v[4:7]
	v_mfma_f32_16x16x32_bf16 v[0:3], v[152:155], v[184:187], v[0:3]
	v_mfma_f32_16x16x32_bf16 v[52:55], v[148:151], v[164:167], v[52:55]
	v_mfma_f32_16x16x32_bf16 v[48:51], v[156:159], v[164:167], v[48:51]
	v_mfma_f32_16x16x32_bf16 v[36:39], v[148:151], v[172:175], v[36:39]
	v_mfma_f32_16x16x32_bf16 v[32:35], v[156:159], v[172:175], v[32:35]
	v_mfma_f32_16x16x32_bf16 v[20:23], v[148:151], v[180:183], v[20:23]
	v_mfma_f32_16x16x32_bf16 v[16:19], v[156:159], v[180:183], v[16:19]
	v_mfma_f32_16x16x32_bf16 v[4:7], v[148:151], v[188:191], v[4:7]
	v_mfma_f32_16x16x32_bf16 v[0:3], v[156:159], v[188:191], v[0:3]
	s_barrier
	s_add_u32 s0, s0, 0x100
	s_addc_u32 s1, s1, 0
	s_add_u32 s21, s21, 0x100
	s_addc_u32 s22, s22, 0
	s_cmp_ge_u32 s25, s62
	s_mov_b32 s4, s25
	s_cbranch_scc0 .LBB0_183

.LBB0_318:
	s_add_u32 s36, s2, s0
	s_addc_u32 s37, s3, s1
	s_add_u32 s36, s36, 0x100
	s_addc_u32 s37, s37, 0
	s_add_u32 s72, s25, s0
	s_addc_u32 s73, s66, s1
	s_add_i32 s74, 0, 0x10000
	s_cmpk_eq_i32 s0, 0xf00
	s_cselect_b32 s45, s39, s37
	s_cselect_b32 s44, s67, s36
	v_add_u32_e32 v154, s74, v159
	s_cselect_b32 s37, s35, s73
	s_cselect_b32 s36, s70, s72
	s_add_i32 s75, 0, 0x14000
	ds_read_b128 v[132:135], v154
	ds_read_b128 v[136:139], v154 offset:1024
	ds_read_b128 v[140:143], v154 offset:2048
	ds_read_b128 v[166:169], v154 offset:3072
	v_add_u32_e32 v154, s75, v159
	ds_read_b128 v[170:173], v154
	ds_read_b128 v[174:177], v154 offset:1024
	ds_read_b128 v[178:181], v154 offset:2048
	ds_read_b128 v[182:185], v154 offset:3072
	v_lshl_add_u64 v[154:155], v[128:129], 0, s[0:1]
	s_add_i32 m0, s7, 0xc000
	ds_read_b128 v[186:189], v165
	ds_read_b128 v[190:193], v165 offset:1024
	ds_read_b128 v[194:197], v165 offset:2048
	ds_read_b128 v[210:213], v165 offset:3072
	ds_read_b128 v[214:217], v165 offset:4096
	ds_read_b128 v[218:221], v165 offset:5120
	ds_read_b128 v[222:225], v165 offset:6144
	ds_read_b128 v[226:229], v165 offset:7168
	global_load_lds_dwordx4 v[154:155], off
	v_lshl_add_u64 v[154:155], v[130:131], 0, s[0:1]
	s_add_i32 m0, s7, 0xe000
	s_nop 0
	global_load_lds_dwordx4 v[154:155], off
	s_waitcnt vmcnt(8)
	s_waitcnt lgkmcnt(0)
	s_barrier
	v_mfma_f32_16x16x32_bf16 v[124:127], v[132:135], v[186:189], v[124:127]
	v_mfma_f32_16x16x32_bf16 v[120:123], v[140:143], v[186:189], v[120:123]
	v_mfma_f32_16x16x32_bf16 v[116:119], v[132:135], v[194:197], v[116:119]
	v_mfma_f32_16x16x32_bf16 v[112:115], v[140:143], v[194:197], v[112:115]
	v_mfma_f32_16x16x32_bf16 v[108:111], v[132:135], v[214:217], v[108:111]
	v_mfma_f32_16x16x32_bf16 v[104:107], v[140:143], v[214:217], v[104:107]
	v_mfma_f32_16x16x32_bf16 v[100:103], v[132:135], v[222:225], v[100:103]
	v_mfma_f32_16x16x32_bf16 v[96:99], v[140:143], v[222:225], v[96:99]
	v_mfma_f32_16x16x32_bf16 v[124:127], v[136:139], v[190:193], v[124:127]
	v_mfma_f32_16x16x32_bf16 v[120:123], v[166:169], v[190:193], v[120:123]
	v_mfma_f32_16x16x32_bf16 v[116:119], v[136:139], v[210:213], v[116:119]
	v_mfma_f32_16x16x32_bf16 v[112:115], v[166:169], v[210:213], v[112:115]
	v_mfma_f32_16x16x32_bf16 v[108:111], v[136:139], v[218:221], v[108:111]
	v_mfma_f32_16x16x32_bf16 v[104:107], v[166:169], v[218:221], v[104:107]
	v_mfma_f32_16x16x32_bf16 v[100:103], v[136:139], v[226:229], v[100:103]
	v_mfma_f32_16x16x32_bf16 v[96:99], v[166:169], v[226:229], v[96:99]
	v_mfma_f32_16x16x32_bf16 v[92:95], v[170:173], v[186:189], v[92:95]
	v_mfma_f32_16x16x32_bf16 v[88:91], v[178:181], v[186:189], v[88:91]
	v_mfma_f32_16x16x32_bf16 v[84:87], v[170:173], v[194:197], v[84:87]
	v_mfma_f32_16x16x32_bf16 v[80:83], v[178:181], v[194:197], v[80:83]
	v_mfma_f32_16x16x32_bf16 v[76:79], v[170:173], v[214:217], v[76:79]
	v_mfma_f32_16x16x32_bf16 v[72:75], v[178:181], v[214:217], v[72:75]
	v_mfma_f32_16x16x32_bf16 v[68:71], v[170:173], v[222:225], v[68:71]
	v_mfma_f32_16x16x32_bf16 v[64:67], v[178:181], v[222:225], v[64:67]
	v_mfma_f32_16x16x32_bf16 v[92:95], v[174:177], v[190:193], v[92:95]
	v_mfma_f32_16x16x32_bf16 v[88:91], v[182:185], v[190:193], v[88:91]
	v_mfma_f32_16x16x32_bf16 v[84:87], v[174:177], v[210:213], v[84:87]
	v_mfma_f32_16x16x32_bf16 v[80:83], v[182:185], v[210:213], v[80:83]
	v_mfma_f32_16x16x32_bf16 v[76:79], v[174:177], v[218:221], v[76:79]
	v_mfma_f32_16x16x32_bf16 v[72:75], v[182:185], v[218:221], v[72:75]
	v_mfma_f32_16x16x32_bf16 v[68:71], v[174:177], v[226:229], v[68:71]
	v_mfma_f32_16x16x32_bf16 v[64:67], v[182:185], v[226:229], v[64:67]
	s_barrier
	s_add_i32 s72, s74, s29
	v_lshl_add_u64 v[154:155], s[36:37], 0, v[204:205]
	s_mov_b32 m0, s72
	ds_read_b128 v[186:189], v165 offset:16384
	ds_read_b128 v[190:193], v165 offset:17408
	ds_read_b128 v[194:197], v165 offset:18432
	ds_read_b128 v[210:213], v165 offset:19456
	ds_read_b128 v[214:217], v165 offset:20480
	ds_read_b128 v[218:221], v165 offset:21504
	ds_read_b128 v[222:225], v165 offset:22528
	ds_read_b128 v[226:229], v165 offset:23552
	global_load_lds_dwordx4 v[154:155], off
	s_add_i32 m0, s72, 0x2000
	s_add_u32 s72, s36, 0x80000
	v_lshl_add_u64 v[198:199], s[36:37], 0, v[148:149]
	s_addc_u32 s73, s37, 0
	s_add_i32 s74, s75, s29
	global_load_lds_dwordx4 v[198:199], off
	v_lshl_add_u64 v[230:231], s[72:73], 0, v[204:205]
	s_mov_b32 m0, s74
	v_lshl_add_u64 v[232:233], s[44:45], 0, v[146:147]
	global_load_lds_dwordx4 v[230:231], off
	v_lshl_add_u64 v[230:231], s[72:73], 0, v[148:149]
	s_add_i32 m0, s74, 0x2000
	s_nop 0
	global_load_lds_dwordx4 v[230:231], off
	v_lshl_add_u64 v[230:231], s[44:45], 0, v[144:145]
	s_mov_b32 m0, s7
	s_nop 0
	global_load_lds_dwordx4 v[230:231], off
	s_mov_b32 m0, s9
	s_nop 0
	global_load_lds_dwordx4 v[232:233], off
	s_waitcnt vmcnt(8)
	s_waitcnt lgkmcnt(0)
	s_barrier
	v_mfma_f32_16x16x32_bf16 v[60:63], v[132:135], v[186:189], v[60:63]
	v_mfma_f32_16x16x32_bf16 v[56:59], v[140:143], v[186:189], v[56:59]
	v_mfma_f32_16x16x32_bf16 v[52:55], v[132:135], v[194:197], v[52:55]
	v_mfma_f32_16x16x32_bf16 v[48:51], v[140:143], v[194:197], v[48:51]
	v_mfma_f32_16x16x32_bf16 v[44:47], v[132:135], v[214:217], v[44:47]
	v_mfma_f32_16x16x32_bf16 v[40:43], v[140:143], v[214:217], v[40:43]
	v_mfma_f32_16x16x32_bf16 v[36:39], v[132:135], v[222:225], v[36:39]
	v_mfma_f32_16x16x32_bf16 v[32:35], v[140:143], v[222:225], v[32:35]
	v_mfma_f32_16x16x32_bf16 v[60:63], v[136:139], v[190:193], v[60:63]
	v_mfma_f32_16x16x32_bf16 v[56:59], v[166:169], v[190:193], v[56:59]
	v_mfma_f32_16x16x32_bf16 v[52:55], v[136:139], v[210:213], v[52:55]
	v_mfma_f32_16x16x32_bf16 v[48:51], v[166:169], v[210:213], v[48:51]
	v_mfma_f32_16x16x32_bf16 v[44:47], v[136:139], v[218:221], v[44:47]
	v_mfma_f32_16x16x32_bf16 v[40:43], v[166:169], v[218:221], v[40:43]
	v_mfma_f32_16x16x32_bf16 v[36:39], v[136:139], v[226:229], v[36:39]
	v_mfma_f32_16x16x32_bf16 v[32:35], v[166:169], v[226:229], v[32:35]
	v_mfma_f32_16x16x32_bf16 v[28:31], v[170:173], v[186:189], v[28:31]
	v_mfma_f32_16x16x32_bf16 v[24:27], v[178:181], v[186:189], v[24:27]
	v_mfma_f32_16x16x32_bf16 v[20:23], v[170:173], v[194:197], v[20:23]
	v_mfma_f32_16x16x32_bf16 v[16:19], v[178:181], v[194:197], v[16:19]
	v_mfma_f32_16x16x32_bf16 v[12:15], v[170:173], v[214:217], v[12:15]
	v_mfma_f32_16x16x32_bf16 v[8:11], v[178:181], v[214:217], v[8:11]
	v_mfma_f32_16x16x32_bf16 v[4:7], v[170:173], v[222:225], v[4:7]
	v_mfma_f32_16x16x32_bf16 v[0:3], v[178:181], v[222:225], v[0:3]
	v_mfma_f32_16x16x32_bf16 v[28:31], v[174:177], v[190:193], v[28:31]
	v_mfma_f32_16x16x32_bf16 v[24:27], v[182:185], v[190:193], v[24:27]
	v_mfma_f32_16x16x32_bf16 v[20:23], v[174:177], v[210:213], v[20:23]
	v_mfma_f32_16x16x32_bf16 v[16:19], v[182:185], v[210:213], v[16:19]
	v_mfma_f32_16x16x32_bf16 v[12:15], v[174:177], v[218:221], v[12:15]
	v_mfma_f32_16x16x32_bf16 v[8:11], v[182:185], v[218:221], v[8:11]
	v_mfma_f32_16x16x32_bf16 v[4:7], v[174:177], v[226:229], v[4:7]
	v_mfma_f32_16x16x32_bf16 v[0:3], v[182:185], v[226:229], v[0:3]
	s_barrier
	s_add_i32 s72, 0, 0x18000
	v_add_u32_e32 v156, s72, v159
	s_add_i32 s73, 0, 0x1c000
	ds_read_b128 v[132:135], v156
	ds_read_b128 v[136:139], v156 offset:1024
	ds_read_b128 v[140:143], v156 offset:2048
	ds_read_b128 v[166:169], v156 offset:3072
	v_add_u32_e32 v156, s73, v159
	ds_read_b128 v[170:173], v156
	ds_read_b128 v[174:177], v156 offset:1024
	ds_read_b128 v[178:181], v156 offset:2048
	ds_read_b128 v[182:185], v156 offset:3072
	s_add_u32 s44, s44, 0x80000
	s_addc_u32 s45, s45, 0
	s_mov_b32 m0, s49
	v_lshl_add_u64 v[248:249], s[44:45], 0, v[144:145]
	ds_read_b128 v[186:189], v165 offset:32768
	ds_read_b128 v[190:193], v165 offset:33792
	ds_read_b128 v[194:197], v165 offset:34816
	ds_read_b128 v[210:213], v165 offset:35840
	ds_read_b128 v[214:217], v165 offset:36864
	ds_read_b128 v[218:221], v165 offset:37888
	ds_read_b128 v[222:225], v165 offset:38912
	ds_read_b128 v[226:229], v165 offset:39936
	global_load_lds_dwordx4 v[248:249], off
	v_lshl_add_u64 v[248:249], s[44:45], 0, v[146:147]
	s_mov_b32 m0, s50
	s_nop 0
	global_load_lds_dwordx4 v[248:249], off
	s_waitcnt vmcnt(8)
	s_waitcnt lgkmcnt(0)
	s_barrier
	v_mfma_f32_16x16x32_bf16 v[124:127], v[132:135], v[186:189], v[124:127]
	v_mfma_f32_16x16x32_bf16 v[120:123], v[140:143], v[186:189], v[120:123]
	v_mfma_f32_16x16x32_bf16 v[116:119], v[132:135], v[194:197], v[116:119]
	v_mfma_f32_16x16x32_bf16 v[112:115], v[140:143], v[194:197], v[112:115]
	v_mfma_f32_16x16x32_bf16 v[108:111], v[132:135], v[214:217], v[108:111]
	v_mfma_f32_16x16x32_bf16 v[104:107], v[140:143], v[214:217], v[104:107]
	v_mfma_f32_16x16x32_bf16 v[100:103], v[132:135], v[222:225], v[100:103]
	v_mfma_f32_16x16x32_bf16 v[96:99], v[140:143], v[222:225], v[96:99]
	v_mfma_f32_16x16x32_bf16 v[124:127], v[136:139], v[190:193], v[124:127]
	v_mfma_f32_16x16x32_bf16 v[120:123], v[166:169], v[190:193], v[120:123]
	v_mfma_f32_16x16x32_bf16 v[116:119], v[136:139], v[210:213], v[116:119]
	v_mfma_f32_16x16x32_bf16 v[112:115], v[166:169], v[210:213], v[112:115]
	v_mfma_f32_16x16x32_bf16 v[108:111], v[136:139], v[218:221], v[108:111]
	v_mfma_f32_16x16x32_bf16 v[104:107], v[166:169], v[218:221], v[104:107]
	v_mfma_f32_16x16x32_bf16 v[100:103], v[136:139], v[226:229], v[100:103]
	v_mfma_f32_16x16x32_bf16 v[96:99], v[166:169], v[226:229], v[96:99]
	v_mfma_f32_16x16x32_bf16 v[92:95], v[170:173], v[186:189], v[92:95]
	v_mfma_f32_16x16x32_bf16 v[88:91], v[178:181], v[186:189], v[88:91]
	v_mfma_f32_16x16x32_bf16 v[84:87], v[170:173], v[194:197], v[84:87]
	v_mfma_f32_16x16x32_bf16 v[80:83], v[178:181], v[194:197], v[80:83]
	v_mfma_f32_16x16x32_bf16 v[76:79], v[170:173], v[214:217], v[76:79]
	v_mfma_f32_16x16x32_bf16 v[72:75], v[178:181], v[214:217], v[72:75]
	v_mfma_f32_16x16x32_bf16 v[68:71], v[170:173], v[222:225], v[68:71]
	v_mfma_f32_16x16x32_bf16 v[64:67], v[178:181], v[222:225], v[64:67]
	v_mfma_f32_16x16x32_bf16 v[92:95], v[174:177], v[190:193], v[92:95]
	v_mfma_f32_16x16x32_bf16 v[88:91], v[182:185], v[190:193], v[88:91]
	v_mfma_f32_16x16x32_bf16 v[84:87], v[174:177], v[210:213], v[84:87]
	v_mfma_f32_16x16x32_bf16 v[80:83], v[182:185], v[210:213], v[80:83]
	v_mfma_f32_16x16x32_bf16 v[76:79], v[174:177], v[218:221], v[76:79]
	v_mfma_f32_16x16x32_bf16 v[72:75], v[182:185], v[218:221], v[72:75]
	v_mfma_f32_16x16x32_bf16 v[68:71], v[174:177], v[226:229], v[68:71]
	v_mfma_f32_16x16x32_bf16 v[64:67], v[182:185], v[226:229], v[64:67]
	s_barrier
	s_add_i32 s44, s72, s29
	v_lshl_add_u64 v[154:155], v[154:155], 0, s[12:13]
	s_mov_b32 m0, s44
	ds_read_b128 v[186:189], v165 offset:49152
	ds_read_b128 v[190:193], v165 offset:50176
	ds_read_b128 v[194:197], v165 offset:51200
	ds_read_b128 v[210:213], v165 offset:52224
	ds_read_b128 v[214:217], v165 offset:53248
	ds_read_b128 v[218:221], v165 offset:54272
	ds_read_b128 v[222:225], v165 offset:55296
	ds_read_b128 v[226:229], v165 offset:56320
	global_load_lds_dwordx4 v[154:155], off
	s_add_i32 m0, s44, 0x2000
	s_add_u32 s36, s36, 0x80080
	v_lshl_add_u64 v[154:155], v[198:199], 0, s[12:13]
	s_addc_u32 s37, s37, 0
	s_add_i32 s44, s73, s29
	global_load_lds_dwordx4 v[154:155], off
	v_lshl_add_u64 v[154:155], s[36:37], 0, v[204:205]
	s_mov_b32 m0, s44
	s_nop 0
	global_load_lds_dwordx4 v[154:155], off
	v_lshl_add_u64 v[154:155], s[36:37], 0, v[148:149]
	s_add_i32 m0, s44, 0x2000
	s_nop 0
	global_load_lds_dwordx4 v[154:155], off
	v_lshl_add_u64 v[154:155], v[230:231], 0, s[12:13]
	s_mov_b32 m0, s54
	s_nop 0
	global_load_lds_dwordx4 v[154:155], off
	v_lshl_add_u64 v[154:155], v[232:233], 0, s[12:13]
	s_mov_b32 m0, s55
	s_nop 0
	global_load_lds_dwordx4 v[154:155], off
	s_waitcnt vmcnt(8)
	s_waitcnt lgkmcnt(0)
	s_barrier
	v_mfma_f32_16x16x32_bf16 v[60:63], v[132:135], v[186:189], v[60:63]
	v_mfma_f32_16x16x32_bf16 v[56:59], v[140:143], v[186:189], v[56:59]
	v_mfma_f32_16x16x32_bf16 v[52:55], v[132:135], v[194:197], v[52:55]
	v_mfma_f32_16x16x32_bf16 v[48:51], v[140:143], v[194:197], v[48:51]
	v_mfma_f32_16x16x32_bf16 v[44:47], v[132:135], v[214:217], v[44:47]
	v_mfma_f32_16x16x32_bf16 v[40:43], v[140:143], v[214:217], v[40:43]
	v_mfma_f32_16x16x32_bf16 v[36:39], v[132:135], v[222:225], v[36:39]
	v_mfma_f32_16x16x32_bf16 v[32:35], v[140:143], v[222:225], v[32:35]
	v_mfma_f32_16x16x32_bf16 v[60:63], v[136:139], v[190:193], v[60:63]
	v_mfma_f32_16x16x32_bf16 v[56:59], v[166:169], v[190:193], v[56:59]
	v_mfma_f32_16x16x32_bf16 v[52:55], v[136:139], v[210:213], v[52:55]
	v_mfma_f32_16x16x32_bf16 v[48:51], v[166:169], v[210:213], v[48:51]
	v_mfma_f32_16x16x32_bf16 v[44:47], v[136:139], v[218:221], v[44:47]
	v_mfma_f32_16x16x32_bf16 v[40:43], v[166:169], v[218:221], v[40:43]
	v_mfma_f32_16x16x32_bf16 v[36:39], v[136:139], v[226:229], v[36:39]
	v_mfma_f32_16x16x32_bf16 v[32:35], v[166:169], v[226:229], v[32:35]
	v_mfma_f32_16x16x32_bf16 v[28:31], v[170:173], v[186:189], v[28:31]
	v_mfma_f32_16x16x32_bf16 v[24:27], v[178:181], v[186:189], v[24:27]
	v_mfma_f32_16x16x32_bf16 v[20:23], v[170:173], v[194:197], v[20:23]
	v_mfma_f32_16x16x32_bf16 v[16:19], v[178:181], v[194:197], v[16:19]
	v_mfma_f32_16x16x32_bf16 v[12:15], v[170:173], v[214:217], v[12:15]
	v_mfma_f32_16x16x32_bf16 v[8:11], v[178:181], v[214:217], v[8:11]
	v_mfma_f32_16x16x32_bf16 v[4:7], v[170:173], v[222:225], v[4:7]
	v_mfma_f32_16x16x32_bf16 v[0:3], v[178:181], v[222:225], v[0:3]
	v_mfma_f32_16x16x32_bf16 v[28:31], v[174:177], v[190:193], v[28:31]
	v_mfma_f32_16x16x32_bf16 v[24:27], v[182:185], v[190:193], v[24:27]
	v_mfma_f32_16x16x32_bf16 v[20:23], v[174:177], v[210:213], v[20:23]
	v_mfma_f32_16x16x32_bf16 v[16:19], v[182:185], v[210:213], v[16:19]
	v_mfma_f32_16x16x32_bf16 v[12:15], v[174:177], v[218:221], v[12:15]
	v_mfma_f32_16x16x32_bf16 v[8:11], v[182:185], v[218:221], v[8:11]
	v_mfma_f32_16x16x32_bf16 v[4:7], v[174:177], v[226:229], v[4:7]
	v_mfma_f32_16x16x32_bf16 v[0:3], v[182:185], v[226:229], v[0:3]
	s_barrier
	s_add_i32 s71, s71, 2
	s_add_u32 s0, s0, 0x100
	s_addc_u32 s1, s1, 0
	s_cmp_gt_u32 s71, 29
	s_cbranch_scc0 .LBB0_318

.LBB0_362:
	s_add_u32 s29, s2, s0
	s_addc_u32 s34, s3, s1
	s_add_u32 s29, s29, 0x100
	s_addc_u32 s34, s34, 0
	s_add_u32 s56, s54, s0
	s_addc_u32 s35, s55, s1
	s_add_i32 s57, 0, 0x10000
	s_cmpk_eq_i32 s0, 0xf00
	s_cselect_b32 s37, s11, s34
	s_cselect_b32 s36, s22, s29
	v_add_u32_e32 v150, s57, v154
	s_cselect_b32 s35, s9, s35
	s_cselect_b32 s34, s25, s56
	s_add_i32 s29, 0, 0x14000
	ds_read_b128 v[142:145], v150
	ds_read_b128 v[146:149], v150 offset:1024
	ds_read_b128 v[160:163], v150 offset:2048
	ds_read_b128 v[164:167], v150 offset:3072
	v_add_u32_e32 v150, s29, v154
	ds_read_b128 v[168:171], v150
	ds_read_b128 v[172:175], v150 offset:1024
	ds_read_b128 v[176:179], v150 offset:2048
	ds_read_b128 v[180:183], v150 offset:3072
	v_lshl_add_u64 v[150:151], v[138:139], 0, s[0:1]
	s_add_i32 m0, s41, 0xc000
	ds_read_b128 v[184:187], v159
	ds_read_b128 v[188:191], v159 offset:1024
	ds_read_b128 v[192:195], v159 offset:2048
	ds_read_b128 v[196:199], v159 offset:3072
	ds_read_b128 v[210:213], v159 offset:4096
	ds_read_b128 v[214:217], v159 offset:5120
	ds_read_b128 v[218:221], v159 offset:6144
	ds_read_b128 v[222:225], v159 offset:7168
	global_load_lds_dwordx4 v[150:151], off
	v_lshl_add_u64 v[150:151], v[140:141], 0, s[0:1]
	s_add_i32 m0, s41, 0xe000
	s_nop 0
	global_load_lds_dwordx4 v[150:151], off
	s_waitcnt vmcnt(8)
	s_waitcnt lgkmcnt(0)
	s_barrier
	v_mfma_f32_16x16x32_bf16 v[124:127], v[142:145], v[184:187], v[124:127]
	v_mfma_f32_16x16x32_bf16 v[120:123], v[160:163], v[184:187], v[120:123]
	v_mfma_f32_16x16x32_bf16 v[116:119], v[142:145], v[192:195], v[116:119]
	v_mfma_f32_16x16x32_bf16 v[112:115], v[160:163], v[192:195], v[112:115]
	v_mfma_f32_16x16x32_bf16 v[108:111], v[142:145], v[210:213], v[108:111]
	v_mfma_f32_16x16x32_bf16 v[104:107], v[160:163], v[210:213], v[104:107]
	v_mfma_f32_16x16x32_bf16 v[100:103], v[142:145], v[218:221], v[100:103]
	v_mfma_f32_16x16x32_bf16 v[96:99], v[160:163], v[218:221], v[96:99]
	v_mfma_f32_16x16x32_bf16 v[124:127], v[146:149], v[188:191], v[124:127]
	v_mfma_f32_16x16x32_bf16 v[120:123], v[164:167], v[188:191], v[120:123]
	v_mfma_f32_16x16x32_bf16 v[116:119], v[146:149], v[196:199], v[116:119]
	v_mfma_f32_16x16x32_bf16 v[112:115], v[164:167], v[196:199], v[112:115]
	v_mfma_f32_16x16x32_bf16 v[108:111], v[146:149], v[214:217], v[108:111]
	v_mfma_f32_16x16x32_bf16 v[104:107], v[164:167], v[214:217], v[104:107]
	v_mfma_f32_16x16x32_bf16 v[100:103], v[146:149], v[222:225], v[100:103]
	v_mfma_f32_16x16x32_bf16 v[96:99], v[164:167], v[222:225], v[96:99]
	v_mfma_f32_16x16x32_bf16 v[92:95], v[168:171], v[184:187], v[92:95]
	v_mfma_f32_16x16x32_bf16 v[88:91], v[176:179], v[184:187], v[88:91]
	v_mfma_f32_16x16x32_bf16 v[84:87], v[168:171], v[192:195], v[84:87]
	v_mfma_f32_16x16x32_bf16 v[80:83], v[176:179], v[192:195], v[80:83]
	v_mfma_f32_16x16x32_bf16 v[76:79], v[168:171], v[210:213], v[76:79]
	v_mfma_f32_16x16x32_bf16 v[72:75], v[176:179], v[210:213], v[72:75]
	v_mfma_f32_16x16x32_bf16 v[68:71], v[168:171], v[218:221], v[68:71]
	v_mfma_f32_16x16x32_bf16 v[64:67], v[176:179], v[218:221], v[64:67]
	v_mfma_f32_16x16x32_bf16 v[92:95], v[172:175], v[188:191], v[92:95]
	v_mfma_f32_16x16x32_bf16 v[88:91], v[180:183], v[188:191], v[88:91]
	v_mfma_f32_16x16x32_bf16 v[84:87], v[172:175], v[196:199], v[84:87]
	v_mfma_f32_16x16x32_bf16 v[80:83], v[180:183], v[196:199], v[80:83]
	v_mfma_f32_16x16x32_bf16 v[76:79], v[172:175], v[214:217], v[76:79]
	v_mfma_f32_16x16x32_bf16 v[72:75], v[180:183], v[214:217], v[72:75]
	v_mfma_f32_16x16x32_bf16 v[68:71], v[172:175], v[222:225], v[68:71]
	v_mfma_f32_16x16x32_bf16 v[64:67], v[180:183], v[222:225], v[64:67]
	s_barrier
	s_add_i32 s56, s57, s38
	v_lshl_add_u64 v[150:151], s[34:35], 0, v[204:205]
	s_mov_b32 m0, s56
	ds_read_b128 v[184:187], v159 offset:16384
	ds_read_b128 v[188:191], v159 offset:17408
	ds_read_b128 v[192:195], v159 offset:18432
	ds_read_b128 v[196:199], v159 offset:19456
	ds_read_b128 v[210:213], v159 offset:20480
	ds_read_b128 v[214:217], v159 offset:21504
	ds_read_b128 v[218:221], v159 offset:22528
	ds_read_b128 v[222:225], v159 offset:23552
	global_load_lds_dwordx4 v[150:151], off
	s_add_i32 m0, s56, 0x2000
	s_add_u32 s56, s34, 0x80000
	v_lshl_add_u64 v[226:227], s[34:35], 0, v[128:129]
	s_addc_u32 s57, s35, 0
	s_add_i32 s29, s29, s38
	global_load_lds_dwordx4 v[226:227], off
	v_lshl_add_u64 v[228:229], s[56:57], 0, v[204:205]
	s_mov_b32 m0, s29
	v_lshl_add_u64 v[230:231], s[36:37], 0, v[130:131]
	global_load_lds_dwordx4 v[228:229], off
	v_lshl_add_u64 v[228:229], s[56:57], 0, v[128:129]
	s_add_i32 m0, s29, 0x2000
	s_nop 0
	global_load_lds_dwordx4 v[228:229], off
	v_lshl_add_u64 v[228:229], s[36:37], 0, v[132:133]
	s_mov_b32 m0, s41
	s_nop 0
	global_load_lds_dwordx4 v[228:229], off
	s_mov_b32 m0, s42
	s_nop 0
	global_load_lds_dwordx4 v[230:231], off
	s_waitcnt vmcnt(8)
	s_waitcnt lgkmcnt(0)
	s_barrier
	v_mfma_f32_16x16x32_bf16 v[60:63], v[142:145], v[184:187], v[60:63]
	v_mfma_f32_16x16x32_bf16 v[56:59], v[160:163], v[184:187], v[56:59]
	v_mfma_f32_16x16x32_bf16 v[52:55], v[142:145], v[192:195], v[52:55]
	v_mfma_f32_16x16x32_bf16 v[48:51], v[160:163], v[192:195], v[48:51]
	v_mfma_f32_16x16x32_bf16 v[44:47], v[142:145], v[210:213], v[44:47]
	v_mfma_f32_16x16x32_bf16 v[40:43], v[160:163], v[210:213], v[40:43]
	v_mfma_f32_16x16x32_bf16 v[36:39], v[142:145], v[218:221], v[36:39]
	v_mfma_f32_16x16x32_bf16 v[32:35], v[160:163], v[218:221], v[32:35]
	v_mfma_f32_16x16x32_bf16 v[60:63], v[146:149], v[188:191], v[60:63]
	v_mfma_f32_16x16x32_bf16 v[56:59], v[164:167], v[188:191], v[56:59]
	v_mfma_f32_16x16x32_bf16 v[52:55], v[146:149], v[196:199], v[52:55]
	v_mfma_f32_16x16x32_bf16 v[48:51], v[164:167], v[196:199], v[48:51]
	v_mfma_f32_16x16x32_bf16 v[44:47], v[146:149], v[214:217], v[44:47]
	v_mfma_f32_16x16x32_bf16 v[40:43], v[164:167], v[214:217], v[40:43]
	v_mfma_f32_16x16x32_bf16 v[36:39], v[146:149], v[222:225], v[36:39]
	v_mfma_f32_16x16x32_bf16 v[32:35], v[164:167], v[222:225], v[32:35]
	v_mfma_f32_16x16x32_bf16 v[28:31], v[168:171], v[184:187], v[28:31]
	v_mfma_f32_16x16x32_bf16 v[24:27], v[176:179], v[184:187], v[24:27]
	v_mfma_f32_16x16x32_bf16 v[20:23], v[168:171], v[192:195], v[20:23]
	v_mfma_f32_16x16x32_bf16 v[16:19], v[176:179], v[192:195], v[16:19]
	v_mfma_f32_16x16x32_bf16 v[12:15], v[168:171], v[210:213], v[12:15]
	v_mfma_f32_16x16x32_bf16 v[8:11], v[176:179], v[210:213], v[8:11]
	v_mfma_f32_16x16x32_bf16 v[4:7], v[168:171], v[218:221], v[4:7]
	v_mfma_f32_16x16x32_bf16 v[0:3], v[176:179], v[218:221], v[0:3]
	v_mfma_f32_16x16x32_bf16 v[28:31], v[172:175], v[188:191], v[28:31]
	v_mfma_f32_16x16x32_bf16 v[24:27], v[180:183], v[188:191], v[24:27]
	v_mfma_f32_16x16x32_bf16 v[20:23], v[172:175], v[196:199], v[20:23]
	v_mfma_f32_16x16x32_bf16 v[16:19], v[180:183], v[196:199], v[16:19]
	v_mfma_f32_16x16x32_bf16 v[12:15], v[172:175], v[214:217], v[12:15]
	v_mfma_f32_16x16x32_bf16 v[8:11], v[180:183], v[214:217], v[8:11]
	v_mfma_f32_16x16x32_bf16 v[4:7], v[172:175], v[222:225], v[4:7]
	v_mfma_f32_16x16x32_bf16 v[0:3], v[180:183], v[222:225], v[0:3]
	s_barrier
	s_add_i32 s29, 0, 0x18000
	v_add_u32_e32 v152, s29, v154
	s_add_i32 s56, 0, 0x1c000
	ds_read_b128 v[142:145], v152
	ds_read_b128 v[146:149], v152 offset:1024
	ds_read_b128 v[160:163], v152 offset:2048
	ds_read_b128 v[164:167], v152 offset:3072
	v_add_u32_e32 v152, s56, v154
	ds_read_b128 v[168:171], v152
	ds_read_b128 v[172:175], v152 offset:1024
	ds_read_b128 v[176:179], v152 offset:2048
	ds_read_b128 v[180:183], v152 offset:3072
	s_add_u32 s36, s36, 0x80000
	s_addc_u32 s37, s37, 0
	s_mov_b32 m0, s43
	v_lshl_add_u64 v[232:233], s[36:37], 0, v[132:133]
	ds_read_b128 v[184:187], v159 offset:32768
	ds_read_b128 v[188:191], v159 offset:33792
	ds_read_b128 v[192:195], v159 offset:34816
	ds_read_b128 v[196:199], v159 offset:35840
	ds_read_b128 v[210:213], v159 offset:36864
	ds_read_b128 v[214:217], v159 offset:37888
	ds_read_b128 v[218:221], v159 offset:38912
	ds_read_b128 v[222:225], v159 offset:39936
	global_load_lds_dwordx4 v[232:233], off
	v_lshl_add_u64 v[232:233], s[36:37], 0, v[130:131]
	s_mov_b32 m0, s44
	s_nop 0
	global_load_lds_dwordx4 v[232:233], off
	s_waitcnt vmcnt(8)
	s_waitcnt lgkmcnt(0)
	s_barrier
	v_mfma_f32_16x16x32_bf16 v[124:127], v[142:145], v[184:187], v[124:127]
	v_mfma_f32_16x16x32_bf16 v[120:123], v[160:163], v[184:187], v[120:123]
	v_mfma_f32_16x16x32_bf16 v[116:119], v[142:145], v[192:195], v[116:119]
	v_mfma_f32_16x16x32_bf16 v[112:115], v[160:163], v[192:195], v[112:115]
	v_mfma_f32_16x16x32_bf16 v[108:111], v[142:145], v[210:213], v[108:111]
	v_mfma_f32_16x16x32_bf16 v[104:107], v[160:163], v[210:213], v[104:107]
	v_mfma_f32_16x16x32_bf16 v[100:103], v[142:145], v[218:221], v[100:103]
	v_mfma_f32_16x16x32_bf16 v[96:99], v[160:163], v[218:221], v[96:99]
	v_mfma_f32_16x16x32_bf16 v[124:127], v[146:149], v[188:191], v[124:127]
	v_mfma_f32_16x16x32_bf16 v[120:123], v[164:167], v[188:191], v[120:123]
	v_mfma_f32_16x16x32_bf16 v[116:119], v[146:149], v[196:199], v[116:119]
	v_mfma_f32_16x16x32_bf16 v[112:115], v[164:167], v[196:199], v[112:115]
	v_mfma_f32_16x16x32_bf16 v[108:111], v[146:149], v[214:217], v[108:111]
	v_mfma_f32_16x16x32_bf16 v[104:107], v[164:167], v[214:217], v[104:107]
	v_mfma_f32_16x16x32_bf16 v[100:103], v[146:149], v[222:225], v[100:103]
	v_mfma_f32_16x16x32_bf16 v[96:99], v[164:167], v[222:225], v[96:99]
	v_mfma_f32_16x16x32_bf16 v[92:95], v[168:171], v[184:187], v[92:95]
	v_mfma_f32_16x16x32_bf16 v[88:91], v[176:179], v[184:187], v[88:91]
	v_mfma_f32_16x16x32_bf16 v[84:87], v[168:171], v[192:195], v[84:87]
	v_mfma_f32_16x16x32_bf16 v[80:83], v[176:179], v[192:195], v[80:83]
	v_mfma_f32_16x16x32_bf16 v[76:79], v[168:171], v[210:213], v[76:79]
	v_mfma_f32_16x16x32_bf16 v[72:75], v[176:179], v[210:213], v[72:75]
	v_mfma_f32_16x16x32_bf16 v[68:71], v[168:171], v[218:221], v[68:71]
	v_mfma_f32_16x16x32_bf16 v[64:67], v[176:179], v[218:221], v[64:67]
	v_mfma_f32_16x16x32_bf16 v[92:95], v[172:175], v[188:191], v[92:95]
	v_mfma_f32_16x16x32_bf16 v[88:91], v[180:183], v[188:191], v[88:91]
	v_mfma_f32_16x16x32_bf16 v[84:87], v[172:175], v[196:199], v[84:87]
	v_mfma_f32_16x16x32_bf16 v[80:83], v[180:183], v[196:199], v[80:83]
	v_mfma_f32_16x16x32_bf16 v[76:79], v[172:175], v[214:217], v[76:79]
	v_mfma_f32_16x16x32_bf16 v[72:75], v[180:183], v[214:217], v[72:75]
	v_mfma_f32_16x16x32_bf16 v[68:71], v[172:175], v[222:225], v[68:71]
	v_mfma_f32_16x16x32_bf16 v[64:67], v[180:183], v[222:225], v[64:67]
	s_barrier
	s_add_i32 s29, s29, s38
	v_lshl_add_u64 v[150:151], v[150:151], 0, s[12:13]
	s_mov_b32 m0, s29
	ds_read_b128 v[184:187], v159 offset:49152
	ds_read_b128 v[188:191], v159 offset:50176
	ds_read_b128 v[192:195], v159 offset:51200
	ds_read_b128 v[196:199], v159 offset:52224
	ds_read_b128 v[210:213], v159 offset:53248
	ds_read_b128 v[214:217], v159 offset:54272
	ds_read_b128 v[218:221], v159 offset:55296
	ds_read_b128 v[222:225], v159 offset:56320
	global_load_lds_dwordx4 v[150:151], off
	s_add_i32 m0, s29, 0x2000
	s_add_u32 s34, s34, 0x80080
	v_lshl_add_u64 v[150:151], v[226:227], 0, s[12:13]
	s_addc_u32 s35, s35, 0
	s_add_i32 s29, s56, s38
	global_load_lds_dwordx4 v[150:151], off
	v_lshl_add_u64 v[150:151], s[34:35], 0, v[204:205]
	s_mov_b32 m0, s29
	s_nop 0
	global_load_lds_dwordx4 v[150:151], off
	v_lshl_add_u64 v[150:151], s[34:35], 0, v[128:129]
	s_add_i32 m0, s29, 0x2000
	s_nop 0
	global_load_lds_dwordx4 v[150:151], off
	v_lshl_add_u64 v[150:151], v[228:229], 0, s[12:13]
	s_mov_b32 m0, s46
	s_nop 0
	global_load_lds_dwordx4 v[150:151], off
	v_lshl_add_u64 v[150:151], v[230:231], 0, s[12:13]
	s_mov_b32 m0, s47
	s_nop 0
	global_load_lds_dwordx4 v[150:151], off
	s_waitcnt vmcnt(8)
	s_waitcnt lgkmcnt(0)
	s_barrier
	v_mfma_f32_16x16x32_bf16 v[60:63], v[142:145], v[184:187], v[60:63]
	v_mfma_f32_16x16x32_bf16 v[56:59], v[160:163], v[184:187], v[56:59]
	v_mfma_f32_16x16x32_bf16 v[52:55], v[142:145], v[192:195], v[52:55]
	v_mfma_f32_16x16x32_bf16 v[48:51], v[160:163], v[192:195], v[48:51]
	v_mfma_f32_16x16x32_bf16 v[44:47], v[142:145], v[210:213], v[44:47]
	v_mfma_f32_16x16x32_bf16 v[40:43], v[160:163], v[210:213], v[40:43]
	v_mfma_f32_16x16x32_bf16 v[36:39], v[142:145], v[218:221], v[36:39]
	v_mfma_f32_16x16x32_bf16 v[32:35], v[160:163], v[218:221], v[32:35]
	v_mfma_f32_16x16x32_bf16 v[60:63], v[146:149], v[188:191], v[60:63]
	v_mfma_f32_16x16x32_bf16 v[56:59], v[164:167], v[188:191], v[56:59]
	v_mfma_f32_16x16x32_bf16 v[52:55], v[146:149], v[196:199], v[52:55]
	v_mfma_f32_16x16x32_bf16 v[48:51], v[164:167], v[196:199], v[48:51]
	v_mfma_f32_16x16x32_bf16 v[44:47], v[146:149], v[214:217], v[44:47]
	v_mfma_f32_16x16x32_bf16 v[40:43], v[164:167], v[214:217], v[40:43]
	v_mfma_f32_16x16x32_bf16 v[36:39], v[146:149], v[222:225], v[36:39]
	v_mfma_f32_16x16x32_bf16 v[32:35], v[164:167], v[222:225], v[32:35]
	v_mfma_f32_16x16x32_bf16 v[28:31], v[168:171], v[184:187], v[28:31]
	v_mfma_f32_16x16x32_bf16 v[24:27], v[176:179], v[184:187], v[24:27]
	v_mfma_f32_16x16x32_bf16 v[20:23], v[168:171], v[192:195], v[20:23]
	v_mfma_f32_16x16x32_bf16 v[16:19], v[176:179], v[192:195], v[16:19]
	v_mfma_f32_16x16x32_bf16 v[12:15], v[168:171], v[210:213], v[12:15]
	v_mfma_f32_16x16x32_bf16 v[8:11], v[176:179], v[210:213], v[8:11]
	v_mfma_f32_16x16x32_bf16 v[4:7], v[168:171], v[218:221], v[4:7]
	v_mfma_f32_16x16x32_bf16 v[0:3], v[176:179], v[218:221], v[0:3]
	v_mfma_f32_16x16x32_bf16 v[28:31], v[172:175], v[188:191], v[28:31]
	v_mfma_f32_16x16x32_bf16 v[24:27], v[180:183], v[188:191], v[24:27]
	v_mfma_f32_16x16x32_bf16 v[20:23], v[172:175], v[196:199], v[20:23]
	v_mfma_f32_16x16x32_bf16 v[16:19], v[180:183], v[196:199], v[16:19]
	v_mfma_f32_16x16x32_bf16 v[12:15], v[172:175], v[214:217], v[12:15]
	v_mfma_f32_16x16x32_bf16 v[8:11], v[180:183], v[214:217], v[8:11]
	v_mfma_f32_16x16x32_bf16 v[4:7], v[172:175], v[222:225], v[4:7]
	v_mfma_f32_16x16x32_bf16 v[0:3], v[180:183], v[222:225], v[0:3]
	s_barrier
	s_add_i32 s28, s28, 2
	s_add_u32 s0, s0, 0x100
	s_addc_u32 s1, s1, 0
	s_cmp_gt_u32 s28, 29
	s_cbranch_scc0 .LBB0_362
